# GEMM K-loop heads: fragment ds_reads issued first, pointer/next-unit select SALU block moved behind them
# speedup vs baseline: 1.0071x; 1.0071x over previous
; #define PG8_STAGE(bufoff, gbase, voff) do { _Pragma("unroll") for (int _i = 0; _i < 2; ++_i) \
;         __builtin_amdgcn_global_load_lds((const unsigned*)((const char*)(gbase) + (voff)[_i]), (PG8_LAS unsigned*)(lds + (bufoff) + ldsw + _i * 8192), 16, 0, 0); } while (0)
; #define PG8_LDA(dst, b, h) do { _Pragma("unroll") for (int m = 0; m < 4; ++m) _Pragma("unroll") for (int k = 0; k < 2; ++k) dst[m][k] = *(const PG8_LAS bf16x8*)(lds + PG8_SA(b, h) + aoff + m * 2048 + k * 1024); } while (0)
; #define PG8_LDB(dst, b, h) do { _Pragma("unroll") for (int n = 0; n < 2; ++n) _Pragma("unroll") for (int k = 0; k < 2; ++k) dst[n][k] = *(const PG8_LAS bf16x8*)(lds + PG8_SB(b, h) + boff + n * 2048 + k * 1024); } while (0)
; #define PG8_MMA(ai, bj, At, Bt) do { __builtin_amdgcn_s_setprio(1); _Pragma("unroll") for (int m = 0; m < 4; ++m) _Pragma("unroll") for (int n = 0; n < 2; ++n) _Pragma("unroll") for (int k = 0; k < 2; ++k) \
;         acc[ai][bj][m][n] = __builtin_amdgcn_mfma_f32_16x16x32_bf16(Bt[n][k], At[m][k], acc[ai][bj][m][n], 0, 0, 0); __builtin_amdgcn_s_setprio(0); } while (0)
; #define PG8_WAIT_V(n) asm volatile("s_waitcnt vmcnt(" #n ")" ::: "memory")
; template <class Epi, class Sched, bool ALIGN_EPI = false, bool SP2 = false>
; __device__ __forceinline__ void gemm_phase(PG8_LAS unsigned char* lds, const Gemm g, const Sched& S, const Epi& E) {
;     ...
;         const char* nA = has_next ? (const char*)g.A + (size_t)nxt.pm * tstep : cA; const char* nB = has_next ? (const char*)g.Bt + (size_t)nxt.pn * tstep : cB;
;         for (int t = 0; t < nt; t += 2) {
;             const bool last = (t == nt - 2);
;             const char* a1 = cA + (size_t)(t + 1) * kstep;
;             const char* a2 = last ? nA : cA + (size_t)(t + 2) * kstep; const char* b2 = last ? nB : cB + (size_t)(t + 2) * kstep;
;             const char* a3 = a2 + kstep; const char* b3 = b2 + kstep;
;             if (last && has_next) S.a_ready(nxt);
;             if constexpr (SP2) {
;             PG8_LDB(B0, 0, 0); PG8_LDB(B1, 0, 1); PG8_SCHED; PG8_LDA(At, 0, 0); PG8_STAGE(PG8_SA(1, 1), a1 + hstep, voffA);
;             PG8_WAIT_V(8); PG8_WAIT_L(0); PG8_BAR; PG8_MMA(0, 0, At, B0); PG8_MMA(0, 1, At, B1); PG8_BAR; PG8_SCHED;
;             PG8_LDA(At, 0, 1); PG8_STAGE(PG8_SB(0, 0), b2, voffB); PG8_STAGE(PG8_SB(0, 1), b2 + hstep, voffB); PG8_STAGE(PG8_SA(0, 0), a2, voffA);
.LBB0_607:
	s_add_i32 s60, 0, 0x10000
	s_add_i32 s62, 0, 0x14000
	v_add_u32_e32 v146, s60, v148
	ds_read_b128 v[142:145], v146
	ds_read_b128 v[152:155], v146 offset:1024
	ds_read_b128 v[156:159], v146 offset:2048
	ds_read_b128 v[160:163], v146 offset:3072
	v_add_u32_e32 v146, s62, v148
	ds_read_b128 v[164:167], v146
	ds_read_b128 v[168:171], v146 offset:1024
	ds_read_b128 v[172:175], v146 offset:2048
	ds_read_b128 v[176:179], v146 offset:3072
	s_add_u32 s30, s28, 0xfffc0080
	s_addc_u32 s31, s29, -1
	s_cmp_eq_u32 s59, 12
	s_cselect_b32 s35, s23, s31
	s_cselect_b32 s34, s33, s30
	s_cselect_b32 s31, s21, s58
	s_cselect_b32 s30, s56, s57
	v_lshl_add_u64 v[192:193], s[28:29], 0, v[138:139]
	s_add_i32 m0, s45, 0xc000
	ds_read_b128 v[180:183], v150
	ds_read_b128 v[184:187], v150 offset:1024
	ds_read_b128 v[188:191], v150 offset:2048
	ds_read_b128 v[204:207], v150 offset:3072
	ds_read_b128 v[220:223], v150 offset:4096
	ds_read_b128 v[224:227], v150 offset:5120
	ds_read_b128 v[228:231], v150 offset:6144
	ds_read_b128 v[232:235], v150 offset:7168
	global_load_lds_dwordx4 v[192:193], off
	v_lshl_add_u64 v[192:193], s[28:29], 0, v[140:141]
	s_add_i32 m0, s45, 0xe000
	s_nop 0
	global_load_lds_dwordx4 v[192:193], off
	s_waitcnt vmcnt(8)
	s_waitcnt lgkmcnt(0)
	s_barrier
	s_setprio 1
	s_waitcnt lgkmcnt(0)
	v_mfma_f32_16x16x32_bf16 v[128:131], v[142:145], v[180:183], v[128:131]
	v_mfma_f32_16x16x32_bf16 v[120:123], v[156:159], v[180:183], v[120:123]
	v_mfma_f32_16x16x32_bf16 v[112:115], v[142:145], v[188:191], v[112:115]
	v_mfma_f32_16x16x32_bf16 v[104:107], v[156:159], v[188:191], v[104:107]
	v_mfma_f32_16x16x32_bf16 v[96:99], v[142:145], v[220:223], v[96:99]
	v_mfma_f32_16x16x32_bf16 v[88:91], v[156:159], v[220:223], v[88:91]
	v_mfma_f32_16x16x32_bf16 v[80:83], v[142:145], v[228:231], v[80:83]
	v_mfma_f32_16x16x32_bf16 v[72:75], v[156:159], v[228:231], v[72:75]
	v_mfma_f32_16x16x32_bf16 v[128:131], v[152:155], v[184:187], v[128:131]
	v_mfma_f32_16x16x32_bf16 v[120:123], v[160:163], v[184:187], v[120:123]
	v_mfma_f32_16x16x32_bf16 v[112:115], v[152:155], v[204:207], v[112:115]
	v_mfma_f32_16x16x32_bf16 v[104:107], v[160:163], v[204:207], v[104:107]
	v_mfma_f32_16x16x32_bf16 v[96:99], v[152:155], v[224:227], v[96:99]
	v_mfma_f32_16x16x32_bf16 v[88:91], v[160:163], v[224:227], v[88:91]
	v_mfma_f32_16x16x32_bf16 v[80:83], v[152:155], v[232:235], v[80:83]
	v_mfma_f32_16x16x32_bf16 v[72:75], v[160:163], v[232:235], v[72:75]
	s_setprio 0
	s_setprio 1
	v_mfma_f32_16x16x32_bf16 v[124:127], v[164:167], v[180:183], v[124:127]
	v_mfma_f32_16x16x32_bf16 v[116:119], v[172:175], v[180:183], v[116:119]
	v_mfma_f32_16x16x32_bf16 v[108:111], v[164:167], v[188:191], v[108:111]
	v_mfma_f32_16x16x32_bf16 v[100:103], v[172:175], v[188:191], v[100:103]
	v_mfma_f32_16x16x32_bf16 v[92:95], v[164:167], v[220:223], v[92:95]
	v_mfma_f32_16x16x32_bf16 v[84:87], v[172:175], v[220:223], v[84:87]
	v_mfma_f32_16x16x32_bf16 v[76:79], v[164:167], v[228:231], v[76:79]
	v_mfma_f32_16x16x32_bf16 v[68:71], v[172:175], v[228:231], v[68:71]
	v_mfma_f32_16x16x32_bf16 v[124:127], v[168:171], v[184:187], v[124:127]
	v_mfma_f32_16x16x32_bf16 v[116:119], v[176:179], v[184:187], v[116:119]
	v_mfma_f32_16x16x32_bf16 v[108:111], v[168:171], v[204:207], v[108:111]
	v_mfma_f32_16x16x32_bf16 v[100:103], v[176:179], v[204:207], v[100:103]
	v_mfma_f32_16x16x32_bf16 v[92:95], v[168:171], v[224:227], v[92:95]
	v_mfma_f32_16x16x32_bf16 v[84:87], v[176:179], v[224:227], v[84:87]
	v_mfma_f32_16x16x32_bf16 v[76:79], v[168:171], v[232:235], v[76:79]
	v_mfma_f32_16x16x32_bf16 v[68:71], v[176:179], v[232:235], v[68:71]
	s_setprio 0
	s_barrier
	s_add_i32 s60, s60, s44
	v_lshl_add_u64 v[192:193], s[30:31], 0, v[2:3]
	s_mov_b32 m0, s60
	ds_read_b128 v[180:183], v150 offset:16384
	ds_read_b128 v[184:187], v150 offset:17408
	ds_read_b128 v[188:191], v150 offset:18432
	ds_read_b128 v[204:207], v150 offset:19456
	ds_read_b128 v[220:223], v150 offset:20480
	ds_read_b128 v[224:227], v150 offset:21504
	ds_read_b128 v[228:231], v150 offset:22528
	ds_read_b128 v[232:235], v150 offset:23552
	global_load_lds_dwordx4 v[192:193], off
	s_add_i32 m0, s60, 0x2000
	s_add_u32 s60, s30, 0x40000
	v_lshl_add_u64 v[194:195], s[30:31], 0, v[132:133]
	s_addc_u32 s61, s31, 0
	s_add_i32 s62, s62, s44
	global_load_lds_dwordx4 v[194:195], off
	v_lshl_add_u64 v[196:197], s[60:61], 0, v[2:3]
	s_mov_b32 m0, s62
	v_lshl_add_u64 v[236:237], s[34:35], 0, v[134:135]
	global_load_lds_dwordx4 v[196:197], off
	v_lshl_add_u64 v[196:197], s[60:61], 0, v[132:133]
	s_add_i32 m0, s62, 0x2000
	s_nop 0
	global_load_lds_dwordx4 v[196:197], off
	v_lshl_add_u64 v[196:197], s[34:35], 0, v[136:137]
	s_mov_b32 m0, s45
	s_nop 0
	global_load_lds_dwordx4 v[196:197], off
	s_mov_b32 m0, s46
	s_nop 0
	global_load_lds_dwordx4 v[236:237], off
	s_waitcnt vmcnt(8)
	s_waitcnt lgkmcnt(0)
	s_barrier
; #define PG8_STAGE(bufoff, gbase, voff) do { _Pragma("unroll") for (int _i = 0; _i < 2; ++_i) \
;         __builtin_amdgcn_global_load_lds((const unsigned*)((const char*)(gbase) + (voff)[_i]), (PG8_LAS unsigned*)(lds + (bufoff) + ldsw + _i * 8192), 16, 0, 0); } while (0)
; #define PG8_LDA(dst, b, h) do { _Pragma("unroll") for (int m = 0; m < 4; ++m) _Pragma("unroll") for (int k = 0; k < 2; ++k) dst[m][k] = *(const PG8_LAS bf16x8*)(lds + PG8_SA(b, h) + aoff + m * 2048 + k * 1024); } while (0)
; #define PG8_LDB(dst, b, h) do { _Pragma("unroll") for (int n = 0; n < 2; ++n) _Pragma("unroll") for (int k = 0; k < 2; ++k) dst[n][k] = *(const PG8_LAS bf16x8*)(lds + PG8_SB(b, h) + boff + n * 2048 + k * 1024); } while (0)
; #define PG8_MMA(ai, bj, At, Bt) do { __builtin_amdgcn_s_setprio(1); _Pragma("unroll") for (int m = 0; m < 4; ++m) _Pragma("unroll") for (int n = 0; n < 2; ++n) _Pragma("unroll") for (int k = 0; k < 2; ++k) \
;         acc[ai][bj][m][n] = __builtin_amdgcn_mfma_f32_16x16x32_bf16(Bt[n][k], At[m][k], acc[ai][bj][m][n], 0, 0, 0); __builtin_amdgcn_s_setprio(0); } while (0)
; #define PG8_WAIT_V(n) asm volatile("s_waitcnt vmcnt(" #n ")" ::: "memory")
; #define PG8_WAIT_L(n) asm volatile("s_waitcnt lgkmcnt(" #n ")" ::: "memory")
; #define PG8_BAR __builtin_amdgcn_s_barrier()
; #define PG8_SCHED __builtin_amdgcn_sched_barrier(0)
; template <class Epi, class Sched, bool ALIGN_EPI = false, bool SP2 = false>
; __device__ __forceinline__ void gemm_phase(PG8_LAS unsigned char* lds, const Gemm g, const Sched& S, const Epi& E) {
;     ...
;             PG8_WAIT_V(8); PG8_WAIT_L(0); PG8_BAR; PG8_MMA(1, 0, At, B0); PG8_MMA(1, 1, At, B1); PG8_BAR; PG8_SCHED;
;             PG8_LDB(B0, 1, 0); PG8_LDB(B1, 1, 1); PG8_SCHED; PG8_LDA(At, 1, 0); PG8_STAGE(PG8_SA(0, 1), a2 + hstep, voffA);
;             PG8_WAIT_V(8); PG8_WAIT_L(0); PG8_BAR; PG8_MMA(0, 0, At, B0); PG8_MMA(0, 1, At, B1); PG8_BAR; PG8_SCHED;
	s_setprio 1
	s_waitcnt lgkmcnt(0)
	v_mfma_f32_16x16x32_bf16 v[64:67], v[142:145], v[180:183], v[64:67]
	v_mfma_f32_16x16x32_bf16 v[56:59], v[156:159], v[180:183], v[56:59]
	v_mfma_f32_16x16x32_bf16 v[48:51], v[142:145], v[188:191], v[48:51]
	v_mfma_f32_16x16x32_bf16 v[40:43], v[156:159], v[188:191], v[40:43]
	v_mfma_f32_16x16x32_bf16 v[32:35], v[142:145], v[220:223], v[32:35]
	v_mfma_f32_16x16x32_bf16 v[24:27], v[156:159], v[220:223], v[24:27]
	v_mfma_f32_16x16x32_bf16 v[16:19], v[142:145], v[228:231], v[16:19]
	v_mfma_f32_16x16x32_bf16 v[8:11], v[156:159], v[228:231], v[8:11]
	v_mfma_f32_16x16x32_bf16 v[64:67], v[152:155], v[184:187], v[64:67]
	v_mfma_f32_16x16x32_bf16 v[56:59], v[160:163], v[184:187], v[56:59]
	v_mfma_f32_16x16x32_bf16 v[48:51], v[152:155], v[204:207], v[48:51]
	v_mfma_f32_16x16x32_bf16 v[40:43], v[160:163], v[204:207], v[40:43]
	v_mfma_f32_16x16x32_bf16 v[32:35], v[152:155], v[224:227], v[32:35]
	v_mfma_f32_16x16x32_bf16 v[24:27], v[160:163], v[224:227], v[24:27]
	v_mfma_f32_16x16x32_bf16 v[16:19], v[152:155], v[232:235], v[16:19]
	v_mfma_f32_16x16x32_bf16 v[8:11], v[160:163], v[232:235], v[8:11]
	s_setprio 0
	s_setprio 1
	v_mfma_f32_16x16x32_bf16 v[60:63], v[164:167], v[180:183], v[60:63]
	v_mfma_f32_16x16x32_bf16 v[52:55], v[172:175], v[180:183], v[52:55]
	v_mfma_f32_16x16x32_bf16 v[44:47], v[164:167], v[188:191], v[44:47]
	v_mfma_f32_16x16x32_bf16 v[36:39], v[172:175], v[188:191], v[36:39]
	v_mfma_f32_16x16x32_bf16 v[28:31], v[164:167], v[220:223], v[28:31]
	v_mfma_f32_16x16x32_bf16 v[20:23], v[172:175], v[220:223], v[20:23]
	v_mfma_f32_16x16x32_bf16 v[12:15], v[164:167], v[228:231], v[12:15]
	v_mfma_f32_16x16x32_bf16 v[4:7], v[172:175], v[228:231], v[4:7]
	v_mfma_f32_16x16x32_bf16 v[60:63], v[168:171], v[184:187], v[60:63]
	v_mfma_f32_16x16x32_bf16 v[52:55], v[176:179], v[184:187], v[52:55]
	v_mfma_f32_16x16x32_bf16 v[44:47], v[168:171], v[204:207], v[44:47]
	v_mfma_f32_16x16x32_bf16 v[36:39], v[176:179], v[204:207], v[36:39]
	v_mfma_f32_16x16x32_bf16 v[28:31], v[168:171], v[224:227], v[28:31]
	v_mfma_f32_16x16x32_bf16 v[20:23], v[176:179], v[224:227], v[20:23]
	v_mfma_f32_16x16x32_bf16 v[12:15], v[168:171], v[232:235], v[12:15]
	v_mfma_f32_16x16x32_bf16 v[4:7], v[176:179], v[232:235], v[4:7]
	s_setprio 0
	s_barrier
	s_add_i32 s60, 0, 0x18000
	v_add_u32_e32 v146, s60, v148
	s_add_i32 s61, 0, 0x1c000
	ds_read_b128 v[142:145], v146
	ds_read_b128 v[152:155], v146 offset:1024
	ds_read_b128 v[156:159], v146 offset:2048
	ds_read_b128 v[160:163], v146 offset:3072
	v_add_u32_e32 v146, s61, v148
	ds_read_b128 v[164:167], v146
	ds_read_b128 v[168:171], v146 offset:1024
	ds_read_b128 v[172:175], v146 offset:2048
	ds_read_b128 v[176:179], v146 offset:3072
	s_add_u32 s34, s34, 0x40000
	s_addc_u32 s35, s35, 0
	s_mov_b32 m0, s47
	v_lshl_add_u64 v[238:239], s[34:35], 0, v[136:137]
	ds_read_b128 v[180:183], v150 offset:32768
	ds_read_b128 v[184:187], v150 offset:33792
	ds_read_b128 v[188:191], v150 offset:34816
	ds_read_b128 v[204:207], v150 offset:35840
	ds_read_b128 v[220:223], v150 offset:36864
	ds_read_b128 v[224:227], v150 offset:37888
	ds_read_b128 v[228:231], v150 offset:38912
	ds_read_b128 v[232:235], v150 offset:39936
	global_load_lds_dwordx4 v[238:239], off
	v_lshl_add_u64 v[238:239], s[34:35], 0, v[134:135]
	s_mov_b32 m0, s50
	s_nop 0
	global_load_lds_dwordx4 v[238:239], off
	s_waitcnt vmcnt(8)
	s_waitcnt lgkmcnt(0)
	s_barrier
	s_setprio 1
	s_waitcnt lgkmcnt(0)
	v_mfma_f32_16x16x32_bf16 v[128:131], v[142:145], v[180:183], v[128:131]
	v_mfma_f32_16x16x32_bf16 v[120:123], v[156:159], v[180:183], v[120:123]
	v_mfma_f32_16x16x32_bf16 v[112:115], v[142:145], v[188:191], v[112:115]
	v_mfma_f32_16x16x32_bf16 v[104:107], v[156:159], v[188:191], v[104:107]
	v_mfma_f32_16x16x32_bf16 v[96:99], v[142:145], v[220:223], v[96:99]
	v_mfma_f32_16x16x32_bf16 v[88:91], v[156:159], v[220:223], v[88:91]
	v_mfma_f32_16x16x32_bf16 v[80:83], v[142:145], v[228:231], v[80:83]
	v_mfma_f32_16x16x32_bf16 v[72:75], v[156:159], v[228:231], v[72:75]
	v_mfma_f32_16x16x32_bf16 v[128:131], v[152:155], v[184:187], v[128:131]
	v_mfma_f32_16x16x32_bf16 v[120:123], v[160:163], v[184:187], v[120:123]
	v_mfma_f32_16x16x32_bf16 v[112:115], v[152:155], v[204:207], v[112:115]
	v_mfma_f32_16x16x32_bf16 v[104:107], v[160:163], v[204:207], v[104:107]
	v_mfma_f32_16x16x32_bf16 v[96:99], v[152:155], v[224:227], v[96:99]
	v_mfma_f32_16x16x32_bf16 v[88:91], v[160:163], v[224:227], v[88:91]
	v_mfma_f32_16x16x32_bf16 v[80:83], v[152:155], v[232:235], v[80:83]
	v_mfma_f32_16x16x32_bf16 v[72:75], v[160:163], v[232:235], v[72:75]
	s_setprio 0
	s_setprio 1
	v_mfma_f32_16x16x32_bf16 v[124:127], v[164:167], v[180:183], v[124:127]
	v_mfma_f32_16x16x32_bf16 v[116:119], v[172:175], v[180:183], v[116:119]
	v_mfma_f32_16x16x32_bf16 v[108:111], v[164:167], v[188:191], v[108:111]
	v_mfma_f32_16x16x32_bf16 v[100:103], v[172:175], v[188:191], v[100:103]
	v_mfma_f32_16x16x32_bf16 v[92:95], v[164:167], v[220:223], v[92:95]
	v_mfma_f32_16x16x32_bf16 v[84:87], v[172:175], v[220:223], v[84:87]
	v_mfma_f32_16x16x32_bf16 v[76:79], v[164:167], v[228:231], v[76:79]
	v_mfma_f32_16x16x32_bf16 v[68:71], v[172:175], v[228:231], v[68:71]
	v_mfma_f32_16x16x32_bf16 v[124:127], v[168:171], v[184:187], v[124:127]
	v_mfma_f32_16x16x32_bf16 v[116:119], v[176:179], v[184:187], v[116:119]
	v_mfma_f32_16x16x32_bf16 v[108:111], v[168:171], v[204:207], v[108:111]
	v_mfma_f32_16x16x32_bf16 v[100:103], v[176:179], v[204:207], v[100:103]
	v_mfma_f32_16x16x32_bf16 v[92:95], v[168:171], v[224:227], v[92:95]
	v_mfma_f32_16x16x32_bf16 v[84:87], v[176:179], v[224:227], v[84:87]
	v_mfma_f32_16x16x32_bf16 v[76:79], v[168:171], v[232:235], v[76:79]
	v_mfma_f32_16x16x32_bf16 v[68:71], v[176:179], v[232:235], v[68:71]
	s_setprio 0
	s_barrier
; #define PG8_STAGE(bufoff, gbase, voff) do { _Pragma("unroll") for (int _i = 0; _i < 2; ++_i) \
;         __builtin_amdgcn_global_load_lds((const unsigned*)((const char*)(gbase) + (voff)[_i]), (PG8_LAS unsigned*)(lds + (bufoff) + ldsw + _i * 8192), 16, 0, 0); } while (0)
; #define PG8_LDA(dst, b, h) do { _Pragma("unroll") for (int m = 0; m < 4; ++m) _Pragma("unroll") for (int k = 0; k < 2; ++k) dst[m][k] = *(const PG8_LAS bf16x8*)(lds + PG8_SA(b, h) + aoff + m * 2048 + k * 1024); } while (0)
; #define PG8_MMA(ai, bj, At, Bt) do { __builtin_amdgcn_s_setprio(1); _Pragma("unroll") for (int m = 0; m < 4; ++m) _Pragma("unroll") for (int n = 0; n < 2; ++n) _Pragma("unroll") for (int k = 0; k < 2; ++k) \
;         acc[ai][bj][m][n] = __builtin_amdgcn_mfma_f32_16x16x32_bf16(Bt[n][k], At[m][k], acc[ai][bj][m][n], 0, 0, 0); __builtin_amdgcn_s_setprio(0); } while (0)
; #define PG8_WAIT_V(n) asm volatile("s_waitcnt vmcnt(" #n ")" ::: "memory")
; #define PG8_WAIT_L(n) asm volatile("s_waitcnt lgkmcnt(" #n ")" ::: "memory")
; #define PG8_BAR __builtin_amdgcn_s_barrier()
; #define PG8_SCHED __builtin_amdgcn_sched_barrier(0)
; template <class Epi, class Sched, bool ALIGN_EPI = false, bool SP2 = false>
; __device__ __forceinline__ void gemm_phase(PG8_LAS unsigned char* lds, const Gemm g, const Sched& S, const Epi& E) {
;     ...
;         for (int t = 0; t < nt; t += 2) {
;             const bool last = (t == nt - 2);
;     ...
;             PG8_LDA(At, 1, 1); PG8_STAGE(PG8_SB(1, 0), b3, voffB); PG8_STAGE(PG8_SB(1, 1), b3 + hstep, voffB); PG8_STAGE(PG8_SA(1, 0), a3, voffA);
;             PG8_WAIT_V(8); PG8_WAIT_L(0); PG8_BAR; PG8_MMA(1, 0, At, B0); PG8_MMA(1, 1, At, B1); PG8_BAR; PG8_SCHED;
	s_add_i32 s34, s60, s44
	v_lshl_add_u64 v[192:193], v[192:193], 0, s[92:93]
	s_mov_b32 m0, s34
	ds_read_b128 v[180:183], v150 offset:49152
	ds_read_b128 v[184:187], v150 offset:50176
	ds_read_b128 v[188:191], v150 offset:51200
	ds_read_b128 v[204:207], v150 offset:52224
	ds_read_b128 v[220:223], v150 offset:53248
	ds_read_b128 v[224:227], v150 offset:54272
	ds_read_b128 v[228:231], v150 offset:55296
	ds_read_b128 v[232:235], v150 offset:56320
	global_load_lds_dwordx4 v[192:193], off
	s_add_i32 m0, s34, 0x2000
	s_add_u32 s30, s30, 0x40080
	v_lshl_add_u64 v[192:193], v[194:195], 0, s[92:93]
	s_addc_u32 s31, s31, 0
	s_add_i32 s34, s61, s44
	global_load_lds_dwordx4 v[192:193], off
	v_lshl_add_u64 v[192:193], s[30:31], 0, v[2:3]
	s_mov_b32 m0, s34
	s_nop 0
	global_load_lds_dwordx4 v[192:193], off
	v_lshl_add_u64 v[192:193], s[30:31], 0, v[132:133]
	s_add_i32 m0, s34, 0x2000
	s_nop 0
	global_load_lds_dwordx4 v[192:193], off
	v_lshl_add_u64 v[192:193], v[196:197], 0, s[92:93]
	s_mov_b32 m0, s51
	s_nop 0
	global_load_lds_dwordx4 v[192:193], off
	v_lshl_add_u64 v[192:193], v[236:237], 0, s[92:93]
	s_mov_b32 m0, s52
	s_nop 0
	global_load_lds_dwordx4 v[192:193], off
	s_waitcnt vmcnt(8)
	s_waitcnt lgkmcnt(0)
	s_barrier
	s_setprio 1
	s_waitcnt lgkmcnt(0)
	v_mfma_f32_16x16x32_bf16 v[64:67], v[142:145], v[180:183], v[64:67]
	v_mfma_f32_16x16x32_bf16 v[56:59], v[156:159], v[180:183], v[56:59]
	v_mfma_f32_16x16x32_bf16 v[48:51], v[142:145], v[188:191], v[48:51]
	v_mfma_f32_16x16x32_bf16 v[40:43], v[156:159], v[188:191], v[40:43]
	v_mfma_f32_16x16x32_bf16 v[32:35], v[142:145], v[220:223], v[32:35]
	v_mfma_f32_16x16x32_bf16 v[24:27], v[156:159], v[220:223], v[24:27]
	v_mfma_f32_16x16x32_bf16 v[16:19], v[142:145], v[228:231], v[16:19]
	v_mfma_f32_16x16x32_bf16 v[8:11], v[156:159], v[228:231], v[8:11]
	v_mfma_f32_16x16x32_bf16 v[64:67], v[152:155], v[184:187], v[64:67]
	v_mfma_f32_16x16x32_bf16 v[56:59], v[160:163], v[184:187], v[56:59]
	v_mfma_f32_16x16x32_bf16 v[48:51], v[152:155], v[204:207], v[48:51]
	v_mfma_f32_16x16x32_bf16 v[40:43], v[160:163], v[204:207], v[40:43]
	v_mfma_f32_16x16x32_bf16 v[32:35], v[152:155], v[224:227], v[32:35]
	v_mfma_f32_16x16x32_bf16 v[24:27], v[160:163], v[224:227], v[24:27]
	v_mfma_f32_16x16x32_bf16 v[16:19], v[152:155], v[232:235], v[16:19]
	v_mfma_f32_16x16x32_bf16 v[8:11], v[160:163], v[232:235], v[8:11]
	s_setprio 0
	s_setprio 1
	v_mfma_f32_16x16x32_bf16 v[60:63], v[164:167], v[180:183], v[60:63]
	v_mfma_f32_16x16x32_bf16 v[52:55], v[172:175], v[180:183], v[52:55]
	v_mfma_f32_16x16x32_bf16 v[44:47], v[164:167], v[188:191], v[44:47]
	v_mfma_f32_16x16x32_bf16 v[36:39], v[172:175], v[188:191], v[36:39]
	v_mfma_f32_16x16x32_bf16 v[28:31], v[164:167], v[220:223], v[28:31]
	v_mfma_f32_16x16x32_bf16 v[20:23], v[172:175], v[220:223], v[20:23]
	v_mfma_f32_16x16x32_bf16 v[12:15], v[164:167], v[228:231], v[12:15]
	v_mfma_f32_16x16x32_bf16 v[4:7], v[172:175], v[228:231], v[4:7]
	v_mfma_f32_16x16x32_bf16 v[60:63], v[168:171], v[184:187], v[60:63]
	v_mfma_f32_16x16x32_bf16 v[52:55], v[176:179], v[184:187], v[52:55]
	v_mfma_f32_16x16x32_bf16 v[44:47], v[168:171], v[204:207], v[44:47]
	v_mfma_f32_16x16x32_bf16 v[36:39], v[176:179], v[204:207], v[36:39]
	v_mfma_f32_16x16x32_bf16 v[28:31], v[168:171], v[224:227], v[28:31]
	v_mfma_f32_16x16x32_bf16 v[20:23], v[176:179], v[224:227], v[20:23]
	v_mfma_f32_16x16x32_bf16 v[12:15], v[168:171], v[232:235], v[12:15]
	v_mfma_f32_16x16x32_bf16 v[4:7], v[176:179], v[232:235], v[4:7]
	s_setprio 0
	s_barrier
	s_add_i32 s59, s59, 2
	s_add_u32 s28, s28, 0x100
	s_addc_u32 s29, s29, 0
	s_add_u32 s57, s57, 0x100
	s_addc_u32 s58, s58, 0
	s_cmp_gt_u32 s59, 13
	s_cbranch_scc0 .LBB0_607
	s_and_b64 vcc, exec, s[18:19]
	s_cbranch_vccz .LBB0_610
	s_barrier

; #define PG8_STAGE(bufoff, gbase, voff) do { _Pragma("unroll") for (int _i = 0; _i < 2; ++_i) \
;         __builtin_amdgcn_global_load_lds((const unsigned*)((const char*)(gbase) + (voff)[_i]), (PG8_LAS unsigned*)(lds + (bufoff) + ldsw + _i * 8192), 16, 0, 0); } while (0)
; #define PG8_LDA(dst, b, h) do { _Pragma("unroll") for (int m = 0; m < 4; ++m) _Pragma("unroll") for (int k = 0; k < 2; ++k) dst[m][k] = *(const PG8_LAS bf16x8*)(lds + PG8_SA(b, h) + aoff + m * 2048 + k * 1024); } while (0)
; #define PG8_LDB(dst, b, h) do { _Pragma("unroll") for (int n = 0; n < 2; ++n) _Pragma("unroll") for (int k = 0; k < 2; ++k) dst[n][k] = *(const PG8_LAS bf16x8*)(lds + PG8_SB(b, h) + boff + n * 2048 + k * 1024); } while (0)
; #define PG8_MMA(ai, bj, At, Bt) do { __builtin_amdgcn_s_setprio(1); _Pragma("unroll") for (int m = 0; m < 4; ++m) _Pragma("unroll") for (int n = 0; n < 2; ++n) _Pragma("unroll") for (int k = 0; k < 2; ++k) \
;         acc[ai][bj][m][n] = __builtin_amdgcn_mfma_f32_16x16x32_bf16(Bt[n][k], At[m][k], acc[ai][bj][m][n], 0, 0, 0); __builtin_amdgcn_s_setprio(0); } while (0)
; #define PG8_WAIT_V(n) asm volatile("s_waitcnt vmcnt(" #n ")" ::: "memory")
; template <class Epi, class Sched, bool ALIGN_EPI = false, bool SP2 = false>
; __device__ __forceinline__ void gemm_phase(PG8_LAS unsigned char* lds, const Gemm g, const Sched& S, const Epi& E) {
;     ...
;         const char* nA = has_next ? (const char*)g.A + (size_t)nxt.pm * tstep : cA; const char* nB = has_next ? (const char*)g.Bt + (size_t)nxt.pn * tstep : cB;
;         for (int t = 0; t < nt; t += 2) {
;             const bool last = (t == nt - 2);
;             const char* a1 = cA + (size_t)(t + 1) * kstep;
;             const char* a2 = last ? nA : cA + (size_t)(t + 2) * kstep; const char* b2 = last ? nB : cB + (size_t)(t + 2) * kstep;
;             const char* a3 = a2 + kstep; const char* b3 = b2 + kstep;
;             if (last && has_next) S.a_ready(nxt);
;             if constexpr (SP2) {
;             PG8_LDB(B0, 0, 0); PG8_LDB(B1, 0, 1); PG8_SCHED; PG8_LDA(At, 0, 0); PG8_STAGE(PG8_SA(1, 1), a1 + hstep, voffA);
;             PG8_WAIT_V(8); PG8_WAIT_L(0); PG8_BAR; PG8_MMA(0, 0, At, B0); PG8_MMA(0, 1, At, B1); PG8_BAR; PG8_SCHED;
;             PG8_LDA(At, 0, 1); PG8_STAGE(PG8_SB(0, 0), b2, voffB); PG8_STAGE(PG8_SB(0, 1), b2 + hstep, voffB); PG8_STAGE(PG8_SA(0, 0), a2, voffA);
.LBB0_638:
	s_add_i32 s58, 0, 0x10000
	s_add_i32 s59, 0, 0x14000
	v_add_u32_e32 v158, s58, v147
	v_add_u32_e32 v174, s59, v147
	ds_read_b128 v[142:145], v158
	ds_read_b128 v[150:153], v158 offset:1024
	ds_read_b128 v[154:157], v158 offset:2048
	ds_read_b128 v[158:161], v158 offset:3072
	ds_read_b128 v[162:165], v174
	ds_read_b128 v[166:169], v174 offset:1024
	ds_read_b128 v[170:173], v174 offset:2048
	ds_read_b128 v[174:177], v174 offset:3072
	s_add_i32 s55, s28, 2
	s_add_u32 s56, s26, 0x80
	s_addc_u32 s29, s27, 0
	s_cmp_eq_u32 s47, s28
	s_cselect_b32 s29, s7, s29
	s_cselect_b32 s28, s6, s56
	s_cselect_b32 s57, s25, s54
	s_cselect_b32 s56, s24, s33
	v_lshl_add_u64 v[194:195], s[26:27], 0, v[138:139]
	s_add_i32 m0, s34, 0xc000
	ds_read_b128 v[178:181], v149
	ds_read_b128 v[182:185], v149 offset:1024
	ds_read_b128 v[186:189], v149 offset:2048
	ds_read_b128 v[190:193], v149 offset:3072
	ds_read_b128 v[204:207], v149 offset:4096
	ds_read_b128 v[220:223], v149 offset:5120
	ds_read_b128 v[224:227], v149 offset:6144
	ds_read_b128 v[228:231], v149 offset:7168
	global_load_lds_dwordx4 v[194:195], off
	v_lshl_add_u64 v[194:195], s[26:27], 0, v[140:141]
	s_add_i32 m0, s34, 0xe000
	s_nop 0
	global_load_lds_dwordx4 v[194:195], off
	s_waitcnt vmcnt(8)
	s_waitcnt lgkmcnt(0)
	s_barrier
	s_setprio 1
	s_waitcnt lgkmcnt(0)
	v_mfma_f32_16x16x32_bf16 v[128:131], v[142:145], v[178:181], v[128:131]
	v_mfma_f32_16x16x32_bf16 v[124:127], v[154:157], v[178:181], v[124:127]
	v_mfma_f32_16x16x32_bf16 v[112:115], v[142:145], v[186:189], v[112:115]
	v_mfma_f32_16x16x32_bf16 v[108:111], v[154:157], v[186:189], v[108:111]
	v_mfma_f32_16x16x32_bf16 v[96:99], v[142:145], v[204:207], v[96:99]
	v_mfma_f32_16x16x32_bf16 v[92:95], v[154:157], v[204:207], v[92:95]
	v_mfma_f32_16x16x32_bf16 v[80:83], v[142:145], v[224:227], v[80:83]
	v_mfma_f32_16x16x32_bf16 v[76:79], v[154:157], v[224:227], v[76:79]
	v_mfma_f32_16x16x32_bf16 v[128:131], v[150:153], v[182:185], v[128:131]
	v_mfma_f32_16x16x32_bf16 v[124:127], v[158:161], v[182:185], v[124:127]
	v_mfma_f32_16x16x32_bf16 v[112:115], v[150:153], v[190:193], v[112:115]
	v_mfma_f32_16x16x32_bf16 v[108:111], v[158:161], v[190:193], v[108:111]
	v_mfma_f32_16x16x32_bf16 v[96:99], v[150:153], v[220:223], v[96:99]
	v_mfma_f32_16x16x32_bf16 v[92:95], v[158:161], v[220:223], v[92:95]
	v_mfma_f32_16x16x32_bf16 v[80:83], v[150:153], v[228:231], v[80:83]
	v_mfma_f32_16x16x32_bf16 v[76:79], v[158:161], v[228:231], v[76:79]
	s_setprio 0
	s_setprio 1
	v_mfma_f32_16x16x32_bf16 v[120:123], v[162:165], v[178:181], v[120:123]
	v_mfma_f32_16x16x32_bf16 v[116:119], v[170:173], v[178:181], v[116:119]
	v_mfma_f32_16x16x32_bf16 v[104:107], v[162:165], v[186:189], v[104:107]
	v_mfma_f32_16x16x32_bf16 v[100:103], v[170:173], v[186:189], v[100:103]
	v_mfma_f32_16x16x32_bf16 v[88:91], v[162:165], v[204:207], v[88:91]
	v_mfma_f32_16x16x32_bf16 v[84:87], v[170:173], v[204:207], v[84:87]
	v_mfma_f32_16x16x32_bf16 v[72:75], v[162:165], v[224:227], v[72:75]
	v_mfma_f32_16x16x32_bf16 v[68:71], v[170:173], v[224:227], v[68:71]
	v_mfma_f32_16x16x32_bf16 v[120:123], v[166:169], v[182:185], v[120:123]
	v_mfma_f32_16x16x32_bf16 v[116:119], v[174:177], v[182:185], v[116:119]
	v_mfma_f32_16x16x32_bf16 v[104:107], v[166:169], v[190:193], v[104:107]
	v_mfma_f32_16x16x32_bf16 v[100:103], v[174:177], v[190:193], v[100:103]
	v_mfma_f32_16x16x32_bf16 v[88:91], v[166:169], v[220:223], v[88:91]
	v_mfma_f32_16x16x32_bf16 v[84:87], v[174:177], v[220:223], v[84:87]
	v_mfma_f32_16x16x32_bf16 v[72:75], v[166:169], v[228:231], v[72:75]
	v_mfma_f32_16x16x32_bf16 v[68:71], v[174:177], v[228:231], v[68:71]
	s_setprio 0
	s_barrier
	s_add_i32 s58, s58, s31
	v_lshl_add_u64 v[194:195], s[56:57], 0, v[2:3]
	s_mov_b32 m0, s58
	ds_read_b128 v[178:181], v149 offset:16384
	ds_read_b128 v[182:185], v149 offset:17408
	ds_read_b128 v[186:189], v149 offset:18432
	ds_read_b128 v[190:193], v149 offset:19456
	ds_read_b128 v[204:207], v149 offset:20480
	ds_read_b128 v[220:223], v149 offset:21504
	ds_read_b128 v[224:227], v149 offset:22528
	ds_read_b128 v[228:231], v149 offset:23552
	global_load_lds_dwordx4 v[194:195], off
	s_add_i32 m0, s58, 0x2000
	v_lshl_add_u64 v[196:197], s[56:57], 0, v[132:133]
	s_add_u32 s56, s56, s10
	s_addc_u32 s57, s57, 0
	s_add_i32 s58, s59, s31
	global_load_lds_dwordx4 v[196:197], off
	v_lshl_add_u64 v[232:233], s[56:57], 0, v[2:3]
	s_mov_b32 m0, s58
	v_lshl_add_u64 v[234:235], s[56:57], 0, v[132:133]
	global_load_lds_dwordx4 v[232:233], off
	s_add_i32 m0, s58, 0x2000
	v_lshl_add_u64 v[236:237], s[28:29], 0, v[136:137]
	global_load_lds_dwordx4 v[234:235], off
	s_mov_b32 m0, s34
	v_lshl_add_u64 v[238:239], s[28:29], 0, v[134:135]
	global_load_lds_dwordx4 v[236:237], off
	s_mov_b32 m0, s35
	s_nop 0
	global_load_lds_dwordx4 v[238:239], off
	s_waitcnt vmcnt(8)
	s_waitcnt lgkmcnt(0)
	s_barrier
; #define PG8_STAGE(bufoff, gbase, voff) do { _Pragma("unroll") for (int _i = 0; _i < 2; ++_i) \
;         __builtin_amdgcn_global_load_lds((const unsigned*)((const char*)(gbase) + (voff)[_i]), (PG8_LAS unsigned*)(lds + (bufoff) + ldsw + _i * 8192), 16, 0, 0); } while (0)
; #define PG8_LDA(dst, b, h) do { _Pragma("unroll") for (int m = 0; m < 4; ++m) _Pragma("unroll") for (int k = 0; k < 2; ++k) dst[m][k] = *(const PG8_LAS bf16x8*)(lds + PG8_SA(b, h) + aoff + m * 2048 + k * 1024); } while (0)
; #define PG8_LDB(dst, b, h) do { _Pragma("unroll") for (int n = 0; n < 2; ++n) _Pragma("unroll") for (int k = 0; k < 2; ++k) dst[n][k] = *(const PG8_LAS bf16x8*)(lds + PG8_SB(b, h) + boff + n * 2048 + k * 1024); } while (0)
; #define PG8_MMA(ai, bj, At, Bt) do { __builtin_amdgcn_s_setprio(1); _Pragma("unroll") for (int m = 0; m < 4; ++m) _Pragma("unroll") for (int n = 0; n < 2; ++n) _Pragma("unroll") for (int k = 0; k < 2; ++k) \
;         acc[ai][bj][m][n] = __builtin_amdgcn_mfma_f32_16x16x32_bf16(Bt[n][k], At[m][k], acc[ai][bj][m][n], 0, 0, 0); __builtin_amdgcn_s_setprio(0); } while (0)
; #define PG8_WAIT_V(n) asm volatile("s_waitcnt vmcnt(" #n ")" ::: "memory")
; #define PG8_WAIT_L(n) asm volatile("s_waitcnt lgkmcnt(" #n ")" ::: "memory")
; #define PG8_BAR __builtin_amdgcn_s_barrier()
; #define PG8_SCHED __builtin_amdgcn_sched_barrier(0)
; template <class Epi, class Sched, bool ALIGN_EPI = false, bool SP2 = false>
; __device__ __forceinline__ void gemm_phase(PG8_LAS unsigned char* lds, const Gemm g, const Sched& S, const Epi& E) {
;     ...
;             PG8_WAIT_V(8); PG8_WAIT_L(0); PG8_BAR; PG8_MMA(1, 0, At, B0); PG8_MMA(1, 1, At, B1); PG8_BAR; PG8_SCHED;
;             PG8_LDB(B0, 1, 0); PG8_LDB(B1, 1, 1); PG8_SCHED; PG8_LDA(At, 1, 0); PG8_STAGE(PG8_SA(0, 1), a2 + hstep, voffA);
;             PG8_WAIT_V(8); PG8_WAIT_L(0); PG8_BAR; PG8_MMA(0, 0, At, B0); PG8_MMA(0, 1, At, B1); PG8_BAR; PG8_SCHED;
	s_setprio 1
	s_waitcnt lgkmcnt(0)
	v_mfma_f32_16x16x32_bf16 v[64:67], v[142:145], v[178:181], v[64:67]
	v_mfma_f32_16x16x32_bf16 v[60:63], v[154:157], v[178:181], v[60:63]
	v_mfma_f32_16x16x32_bf16 v[48:51], v[142:145], v[186:189], v[48:51]
	v_mfma_f32_16x16x32_bf16 v[44:47], v[154:157], v[186:189], v[44:47]
	v_mfma_f32_16x16x32_bf16 v[32:35], v[142:145], v[204:207], v[32:35]
	v_mfma_f32_16x16x32_bf16 v[28:31], v[154:157], v[204:207], v[28:31]
	v_mfma_f32_16x16x32_bf16 v[16:19], v[142:145], v[224:227], v[16:19]
	v_mfma_f32_16x16x32_bf16 v[12:15], v[154:157], v[224:227], v[12:15]
	v_mfma_f32_16x16x32_bf16 v[64:67], v[150:153], v[182:185], v[64:67]
	v_mfma_f32_16x16x32_bf16 v[60:63], v[158:161], v[182:185], v[60:63]
	v_mfma_f32_16x16x32_bf16 v[48:51], v[150:153], v[190:193], v[48:51]
	v_mfma_f32_16x16x32_bf16 v[44:47], v[158:161], v[190:193], v[44:47]
	v_mfma_f32_16x16x32_bf16 v[32:35], v[150:153], v[220:223], v[32:35]
	v_mfma_f32_16x16x32_bf16 v[28:31], v[158:161], v[220:223], v[28:31]
	v_mfma_f32_16x16x32_bf16 v[16:19], v[150:153], v[228:231], v[16:19]
	v_mfma_f32_16x16x32_bf16 v[12:15], v[158:161], v[228:231], v[12:15]
	s_setprio 0
	s_setprio 1
	v_mfma_f32_16x16x32_bf16 v[56:59], v[162:165], v[178:181], v[56:59]
	v_mfma_f32_16x16x32_bf16 v[52:55], v[170:173], v[178:181], v[52:55]
	v_mfma_f32_16x16x32_bf16 v[40:43], v[162:165], v[186:189], v[40:43]
	v_mfma_f32_16x16x32_bf16 v[36:39], v[170:173], v[186:189], v[36:39]
	v_mfma_f32_16x16x32_bf16 v[24:27], v[162:165], v[204:207], v[24:27]
	v_mfma_f32_16x16x32_bf16 v[20:23], v[170:173], v[204:207], v[20:23]
	v_mfma_f32_16x16x32_bf16 v[8:11], v[162:165], v[224:227], v[8:11]
	v_mfma_f32_16x16x32_bf16 v[4:7], v[170:173], v[224:227], v[4:7]
	v_mfma_f32_16x16x32_bf16 v[56:59], v[166:169], v[182:185], v[56:59]
	v_mfma_f32_16x16x32_bf16 v[52:55], v[174:177], v[182:185], v[52:55]
	v_mfma_f32_16x16x32_bf16 v[40:43], v[166:169], v[190:193], v[40:43]
	v_mfma_f32_16x16x32_bf16 v[36:39], v[174:177], v[190:193], v[36:39]
	v_mfma_f32_16x16x32_bf16 v[24:27], v[166:169], v[220:223], v[24:27]
	v_mfma_f32_16x16x32_bf16 v[20:23], v[174:177], v[220:223], v[20:23]
	v_mfma_f32_16x16x32_bf16 v[8:11], v[166:169], v[228:231], v[8:11]
	v_mfma_f32_16x16x32_bf16 v[4:7], v[174:177], v[228:231], v[4:7]
	s_setprio 0
	s_barrier
	s_add_i32 s56, 0, 0x18000
	s_add_i32 s57, 0, 0x1c000
	v_add_u32_e32 v158, s56, v147
	v_add_u32_e32 v174, s57, v147
	ds_read_b128 v[142:145], v158
	ds_read_b128 v[150:153], v158 offset:1024
	ds_read_b128 v[154:157], v158 offset:2048
	ds_read_b128 v[158:161], v158 offset:3072
	ds_read_b128 v[162:165], v174
	ds_read_b128 v[166:169], v174 offset:1024
	ds_read_b128 v[170:173], v174 offset:2048
	ds_read_b128 v[174:177], v174 offset:3072
	s_add_u32 s28, s28, s10
	s_addc_u32 s29, s29, 0
	s_mov_b32 m0, s41
	v_lshl_add_u64 v[240:241], s[28:29], 0, v[136:137]
	ds_read_b128 v[178:181], v149 offset:32768
	ds_read_b128 v[182:185], v149 offset:33792
	ds_read_b128 v[186:189], v149 offset:34816
	ds_read_b128 v[190:193], v149 offset:35840
	ds_read_b128 v[204:207], v149 offset:36864
	ds_read_b128 v[220:223], v149 offset:37888
	ds_read_b128 v[224:227], v149 offset:38912
	ds_read_b128 v[228:231], v149 offset:39936
	global_load_lds_dwordx4 v[240:241], off
	v_lshl_add_u64 v[240:241], s[28:29], 0, v[134:135]
	s_mov_b32 m0, s42
	s_nop 0
	global_load_lds_dwordx4 v[240:241], off
	s_waitcnt vmcnt(8)
	s_waitcnt lgkmcnt(0)
	s_barrier
	s_setprio 1
	s_waitcnt lgkmcnt(0)
	v_mfma_f32_16x16x32_bf16 v[128:131], v[142:145], v[178:181], v[128:131]
	v_mfma_f32_16x16x32_bf16 v[124:127], v[154:157], v[178:181], v[124:127]
	v_mfma_f32_16x16x32_bf16 v[112:115], v[142:145], v[186:189], v[112:115]
	v_mfma_f32_16x16x32_bf16 v[108:111], v[154:157], v[186:189], v[108:111]
	v_mfma_f32_16x16x32_bf16 v[96:99], v[142:145], v[204:207], v[96:99]
	v_mfma_f32_16x16x32_bf16 v[92:95], v[154:157], v[204:207], v[92:95]
	v_mfma_f32_16x16x32_bf16 v[80:83], v[142:145], v[224:227], v[80:83]
	v_mfma_f32_16x16x32_bf16 v[76:79], v[154:157], v[224:227], v[76:79]
	v_mfma_f32_16x16x32_bf16 v[128:131], v[150:153], v[182:185], v[128:131]
	v_mfma_f32_16x16x32_bf16 v[124:127], v[158:161], v[182:185], v[124:127]
	v_mfma_f32_16x16x32_bf16 v[112:115], v[150:153], v[190:193], v[112:115]
	v_mfma_f32_16x16x32_bf16 v[108:111], v[158:161], v[190:193], v[108:111]
	v_mfma_f32_16x16x32_bf16 v[96:99], v[150:153], v[220:223], v[96:99]
	v_mfma_f32_16x16x32_bf16 v[92:95], v[158:161], v[220:223], v[92:95]
	v_mfma_f32_16x16x32_bf16 v[80:83], v[150:153], v[228:231], v[80:83]
	v_mfma_f32_16x16x32_bf16 v[76:79], v[158:161], v[228:231], v[76:79]
	s_setprio 0
	s_setprio 1
	v_mfma_f32_16x16x32_bf16 v[120:123], v[162:165], v[178:181], v[120:123]
	v_mfma_f32_16x16x32_bf16 v[116:119], v[170:173], v[178:181], v[116:119]
	v_mfma_f32_16x16x32_bf16 v[104:107], v[162:165], v[186:189], v[104:107]
	v_mfma_f32_16x16x32_bf16 v[100:103], v[170:173], v[186:189], v[100:103]
	v_mfma_f32_16x16x32_bf16 v[88:91], v[162:165], v[204:207], v[88:91]
	v_mfma_f32_16x16x32_bf16 v[84:87], v[170:173], v[204:207], v[84:87]
	v_mfma_f32_16x16x32_bf16 v[72:75], v[162:165], v[224:227], v[72:75]
	v_mfma_f32_16x16x32_bf16 v[68:71], v[170:173], v[224:227], v[68:71]
	v_mfma_f32_16x16x32_bf16 v[120:123], v[166:169], v[182:185], v[120:123]
	v_mfma_f32_16x16x32_bf16 v[116:119], v[174:177], v[182:185], v[116:119]
	v_mfma_f32_16x16x32_bf16 v[104:107], v[166:169], v[190:193], v[104:107]
	v_mfma_f32_16x16x32_bf16 v[100:103], v[174:177], v[190:193], v[100:103]
	v_mfma_f32_16x16x32_bf16 v[88:91], v[166:169], v[220:223], v[88:91]
	v_mfma_f32_16x16x32_bf16 v[84:87], v[174:177], v[220:223], v[84:87]
	v_mfma_f32_16x16x32_bf16 v[72:75], v[166:169], v[228:231], v[72:75]
	v_mfma_f32_16x16x32_bf16 v[68:71], v[174:177], v[228:231], v[68:71]
	s_setprio 0
	s_barrier
; #define PG8_STAGE(bufoff, gbase, voff) do { _Pragma("unroll") for (int _i = 0; _i < 2; ++_i) \
;         __builtin_amdgcn_global_load_lds((const unsigned*)((const char*)(gbase) + (voff)[_i]), (PG8_LAS unsigned*)(lds + (bufoff) + ldsw + _i * 8192), 16, 0, 0); } while (0)
; #define PG8_LDA(dst, b, h) do { _Pragma("unroll") for (int m = 0; m < 4; ++m) _Pragma("unroll") for (int k = 0; k < 2; ++k) dst[m][k] = *(const PG8_LAS bf16x8*)(lds + PG8_SA(b, h) + aoff + m * 2048 + k * 1024); } while (0)
; #define PG8_MMA(ai, bj, At, Bt) do { __builtin_amdgcn_s_setprio(1); _Pragma("unroll") for (int m = 0; m < 4; ++m) _Pragma("unroll") for (int n = 0; n < 2; ++n) _Pragma("unroll") for (int k = 0; k < 2; ++k) \
;         acc[ai][bj][m][n] = __builtin_amdgcn_mfma_f32_16x16x32_bf16(Bt[n][k], At[m][k], acc[ai][bj][m][n], 0, 0, 0); __builtin_amdgcn_s_setprio(0); } while (0)
; #define PG8_WAIT_V(n) asm volatile("s_waitcnt vmcnt(" #n ")" ::: "memory")
; #define PG8_WAIT_L(n) asm volatile("s_waitcnt lgkmcnt(" #n ")" ::: "memory")
; #define PG8_BAR __builtin_amdgcn_s_barrier()
; #define PG8_SCHED __builtin_amdgcn_sched_barrier(0)
; template <class Epi, class Sched, bool ALIGN_EPI = false, bool SP2 = false>
; __device__ __forceinline__ void gemm_phase(PG8_LAS unsigned char* lds, const Gemm g, const Sched& S, const Epi& E) {
;     ...
;         for (int t = 0; t < nt; t += 2) {
;             const bool last = (t == nt - 2);
;     ...
;             PG8_LDA(At, 1, 1); PG8_STAGE(PG8_SB(1, 0), b3, voffB); PG8_STAGE(PG8_SB(1, 1), b3 + hstep, voffB); PG8_STAGE(PG8_SA(1, 0), a3, voffA);
;             PG8_WAIT_V(8); PG8_WAIT_L(0); PG8_BAR; PG8_MMA(1, 0, At, B0); PG8_MMA(1, 1, At, B1); PG8_BAR; PG8_SCHED;
	s_add_i32 s28, s56, s31
	v_lshl_add_u64 v[194:195], v[194:195], 0, s[92:93]
	s_mov_b32 m0, s28
	ds_read_b128 v[178:181], v149 offset:49152
	ds_read_b128 v[182:185], v149 offset:50176
	ds_read_b128 v[186:189], v149 offset:51200
	ds_read_b128 v[190:193], v149 offset:52224
	ds_read_b128 v[204:207], v149 offset:53248
	ds_read_b128 v[220:223], v149 offset:54272
	ds_read_b128 v[224:227], v149 offset:55296
	ds_read_b128 v[228:231], v149 offset:56320
	global_load_lds_dwordx4 v[194:195], off
	v_lshl_add_u64 v[194:195], v[196:197], 0, s[92:93]
	s_add_i32 m0, s28, 0x2000
	s_add_i32 s28, s57, s31
	global_load_lds_dwordx4 v[194:195], off
	v_lshl_add_u64 v[194:195], v[232:233], 0, s[92:93]
	s_mov_b32 m0, s28
	s_nop 0
	global_load_lds_dwordx4 v[194:195], off
	v_lshl_add_u64 v[194:195], v[234:235], 0, s[92:93]
	s_add_i32 m0, s28, 0x2000
	s_nop 0
	global_load_lds_dwordx4 v[194:195], off
	v_lshl_add_u64 v[194:195], v[236:237], 0, s[92:93]
	s_mov_b32 m0, s45
	s_nop 0
	global_load_lds_dwordx4 v[194:195], off
	v_lshl_add_u64 v[194:195], v[238:239], 0, s[92:93]
	s_mov_b32 m0, s46
	s_nop 0
	global_load_lds_dwordx4 v[194:195], off
	s_waitcnt vmcnt(8)
	s_waitcnt lgkmcnt(0)
	s_barrier
	s_setprio 1
	s_waitcnt lgkmcnt(0)
	v_mfma_f32_16x16x32_bf16 v[64:67], v[142:145], v[178:181], v[64:67]
	v_mfma_f32_16x16x32_bf16 v[60:63], v[154:157], v[178:181], v[60:63]
	v_mfma_f32_16x16x32_bf16 v[48:51], v[142:145], v[186:189], v[48:51]
	v_mfma_f32_16x16x32_bf16 v[44:47], v[154:157], v[186:189], v[44:47]
	v_mfma_f32_16x16x32_bf16 v[32:35], v[142:145], v[204:207], v[32:35]
	v_mfma_f32_16x16x32_bf16 v[28:31], v[154:157], v[204:207], v[28:31]
	v_mfma_f32_16x16x32_bf16 v[16:19], v[142:145], v[224:227], v[16:19]
	v_mfma_f32_16x16x32_bf16 v[12:15], v[154:157], v[224:227], v[12:15]
	v_mfma_f32_16x16x32_bf16 v[64:67], v[150:153], v[182:185], v[64:67]
	v_mfma_f32_16x16x32_bf16 v[60:63], v[158:161], v[182:185], v[60:63]
	v_mfma_f32_16x16x32_bf16 v[48:51], v[150:153], v[190:193], v[48:51]
	v_mfma_f32_16x16x32_bf16 v[44:47], v[158:161], v[190:193], v[44:47]
	v_mfma_f32_16x16x32_bf16 v[32:35], v[150:153], v[220:223], v[32:35]
	v_mfma_f32_16x16x32_bf16 v[28:31], v[158:161], v[220:223], v[28:31]
	v_mfma_f32_16x16x32_bf16 v[16:19], v[150:153], v[228:231], v[16:19]
	v_mfma_f32_16x16x32_bf16 v[12:15], v[158:161], v[228:231], v[12:15]
	s_setprio 0
	s_setprio 1
	v_mfma_f32_16x16x32_bf16 v[56:59], v[162:165], v[178:181], v[56:59]
	v_mfma_f32_16x16x32_bf16 v[52:55], v[170:173], v[178:181], v[52:55]
	v_mfma_f32_16x16x32_bf16 v[40:43], v[162:165], v[186:189], v[40:43]
	v_mfma_f32_16x16x32_bf16 v[36:39], v[170:173], v[186:189], v[36:39]
	v_mfma_f32_16x16x32_bf16 v[24:27], v[162:165], v[204:207], v[24:27]
	v_mfma_f32_16x16x32_bf16 v[20:23], v[170:173], v[204:207], v[20:23]
	v_mfma_f32_16x16x32_bf16 v[8:11], v[162:165], v[224:227], v[8:11]
	v_mfma_f32_16x16x32_bf16 v[4:7], v[170:173], v[224:227], v[4:7]
	v_mfma_f32_16x16x32_bf16 v[56:59], v[166:169], v[182:185], v[56:59]
	v_mfma_f32_16x16x32_bf16 v[52:55], v[174:177], v[182:185], v[52:55]
	v_mfma_f32_16x16x32_bf16 v[40:43], v[166:169], v[190:193], v[40:43]
	v_mfma_f32_16x16x32_bf16 v[36:39], v[174:177], v[190:193], v[36:39]
	v_mfma_f32_16x16x32_bf16 v[24:27], v[166:169], v[220:223], v[24:27]
	v_mfma_f32_16x16x32_bf16 v[20:23], v[174:177], v[220:223], v[20:23]
	v_mfma_f32_16x16x32_bf16 v[8:11], v[166:169], v[228:231], v[8:11]
	v_mfma_f32_16x16x32_bf16 v[4:7], v[174:177], v[228:231], v[4:7]
	s_setprio 0
	s_barrier
	s_add_u32 s26, s26, 0x100
	s_addc_u32 s27, s27, 0
	s_add_u32 s33, s33, 0x100
	s_addc_u32 s54, s54, 0
	s_cmp_ge_u32 s55, s44
	s_mov_b32 s28, s55
	s_cbranch_scc0 .LBB0_638
	s_and_b64 vcc, exec, s[22:23]
	s_cbranch_vccz .LBB0_641
	s_barrier

; #define PG8_STAGE(bufoff, gbase, voff) do { _Pragma("unroll") for (int _i = 0; _i < 2; ++_i) \
;         __builtin_amdgcn_global_load_lds((const unsigned*)((const char*)(gbase) + (voff)[_i]), (PG8_LAS unsigned*)(lds + (bufoff) + ldsw + _i * 8192), 16, 0, 0); } while (0)
; #define PG8_LDA(dst, b, h) do { _Pragma("unroll") for (int m = 0; m < 4; ++m) _Pragma("unroll") for (int k = 0; k < 2; ++k) dst[m][k] = *(const PG8_LAS bf16x8*)(lds + PG8_SA(b, h) + aoff + m * 2048 + k * 1024); } while (0)
; #define PG8_LDB(dst, b, h) do { _Pragma("unroll") for (int n = 0; n < 2; ++n) _Pragma("unroll") for (int k = 0; k < 2; ++k) dst[n][k] = *(const PG8_LAS bf16x8*)(lds + PG8_SB(b, h) + boff + n * 2048 + k * 1024); } while (0)
; #define PG8_MMA(ai, bj, At, Bt) do { __builtin_amdgcn_s_setprio(1); _Pragma("unroll") for (int m = 0; m < 4; ++m) _Pragma("unroll") for (int n = 0; n < 2; ++n) _Pragma("unroll") for (int k = 0; k < 2; ++k) \
;         acc[ai][bj][m][n] = __builtin_amdgcn_mfma_f32_16x16x32_bf16(Bt[n][k], At[m][k], acc[ai][bj][m][n], 0, 0, 0); __builtin_amdgcn_s_setprio(0); } while (0)
; #define PG8_WAIT_V(n) asm volatile("s_waitcnt vmcnt(" #n ")" ::: "memory")
; template <class Epi, class Sched, bool ALIGN_EPI = false, bool SP2 = false>
; __device__ __forceinline__ void gemm_phase(PG8_LAS unsigned char* lds, const Gemm g, const Sched& S, const Epi& E) {
;     ...
;         const char* nA = has_next ? (const char*)g.A + (size_t)nxt.pm * tstep : cA; const char* nB = has_next ? (const char*)g.Bt + (size_t)nxt.pn * tstep : cB;
;         for (int t = 0; t < nt; t += 2) {
;             const bool last = (t == nt - 2);
;             const char* a1 = cA + (size_t)(t + 1) * kstep;
;             const char* a2 = last ? nA : cA + (size_t)(t + 2) * kstep; const char* b2 = last ? nB : cB + (size_t)(t + 2) * kstep;
;             const char* a3 = a2 + kstep; const char* b3 = b2 + kstep;
;             if (last && has_next) S.a_ready(nxt);
;             if constexpr (SP2) {
;             PG8_LDB(B0, 0, 0); PG8_LDB(B1, 0, 1); PG8_SCHED; PG8_LDA(At, 0, 0); PG8_STAGE(PG8_SA(1, 1), a1 + hstep, voffA);
;             PG8_WAIT_V(8); PG8_WAIT_L(0); PG8_BAR; PG8_MMA(0, 0, At, B0); PG8_MMA(0, 1, At, B1); PG8_BAR; PG8_SCHED;
;             PG8_LDA(At, 0, 1); PG8_STAGE(PG8_SB(0, 0), b2, voffB); PG8_STAGE(PG8_SB(0, 1), b2 + hstep, voffB); PG8_STAGE(PG8_SA(0, 0), a2, voffA);
.LBB0_685:
	s_add_i32 s69, 0, 0x10000
	s_add_i32 s73, 0, 0x14000
	v_add_u32_e32 v158, s69, v147
	v_add_u32_e32 v174, s73, v147
	ds_read_b128 v[142:145], v158
	ds_read_b128 v[150:153], v158 offset:1024
	ds_read_b128 v[154:157], v158 offset:2048
	ds_read_b128 v[158:161], v158 offset:3072
	ds_read_b128 v[162:165], v174
	ds_read_b128 v[166:169], v174 offset:1024
	ds_read_b128 v[170:173], v174 offset:2048
	ds_read_b128 v[174:177], v174 offset:3072
	s_add_u32 s44, s42, 0xfffc0080
	s_addc_u32 s45, s43, -1
	s_cmp_eq_u32 s68, 12
	s_cselect_b32 s47, s33, s45
	s_cselect_b32 s46, s35, s44
	s_cselect_b32 s45, s31, s67
	s_cselect_b32 s44, s65, s66
	v_lshl_add_u64 v[194:195], s[42:43], 0, v[138:139]
	s_add_i32 m0, s58, 0xc000
	ds_read_b128 v[178:181], v149
	ds_read_b128 v[182:185], v149 offset:1024
	ds_read_b128 v[186:189], v149 offset:2048
	ds_read_b128 v[190:193], v149 offset:3072
	ds_read_b128 v[204:207], v149 offset:4096
	ds_read_b128 v[220:223], v149 offset:5120
	ds_read_b128 v[224:227], v149 offset:6144
	ds_read_b128 v[228:231], v149 offset:7168
	global_load_lds_dwordx4 v[194:195], off
	v_lshl_add_u64 v[194:195], s[42:43], 0, v[140:141]
	s_add_i32 m0, s58, 0xe000
	s_nop 0
	global_load_lds_dwordx4 v[194:195], off
	s_waitcnt vmcnt(8)
	s_waitcnt lgkmcnt(0)
	s_barrier
	s_setprio 1
	s_waitcnt lgkmcnt(0)
	v_mfma_f32_16x16x32_bf16 v[128:131], v[142:145], v[178:181], v[128:131]
	v_mfma_f32_16x16x32_bf16 v[124:127], v[154:157], v[178:181], v[124:127]
	v_mfma_f32_16x16x32_bf16 v[112:115], v[142:145], v[186:189], v[112:115]
	v_mfma_f32_16x16x32_bf16 v[108:111], v[154:157], v[186:189], v[108:111]
	v_mfma_f32_16x16x32_bf16 v[96:99], v[142:145], v[204:207], v[96:99]
	v_mfma_f32_16x16x32_bf16 v[92:95], v[154:157], v[204:207], v[92:95]
	v_mfma_f32_16x16x32_bf16 v[80:83], v[142:145], v[224:227], v[80:83]
	v_mfma_f32_16x16x32_bf16 v[76:79], v[154:157], v[224:227], v[76:79]
	v_mfma_f32_16x16x32_bf16 v[128:131], v[150:153], v[182:185], v[128:131]
	v_mfma_f32_16x16x32_bf16 v[124:127], v[158:161], v[182:185], v[124:127]
	v_mfma_f32_16x16x32_bf16 v[112:115], v[150:153], v[190:193], v[112:115]
	v_mfma_f32_16x16x32_bf16 v[108:111], v[158:161], v[190:193], v[108:111]
	v_mfma_f32_16x16x32_bf16 v[96:99], v[150:153], v[220:223], v[96:99]
	v_mfma_f32_16x16x32_bf16 v[92:95], v[158:161], v[220:223], v[92:95]
	v_mfma_f32_16x16x32_bf16 v[80:83], v[150:153], v[228:231], v[80:83]
	v_mfma_f32_16x16x32_bf16 v[76:79], v[158:161], v[228:231], v[76:79]
	s_setprio 0
	s_setprio 1
	v_mfma_f32_16x16x32_bf16 v[120:123], v[162:165], v[178:181], v[120:123]
	v_mfma_f32_16x16x32_bf16 v[116:119], v[170:173], v[178:181], v[116:119]
	v_mfma_f32_16x16x32_bf16 v[104:107], v[162:165], v[186:189], v[104:107]
	v_mfma_f32_16x16x32_bf16 v[100:103], v[170:173], v[186:189], v[100:103]
	v_mfma_f32_16x16x32_bf16 v[88:91], v[162:165], v[204:207], v[88:91]
	v_mfma_f32_16x16x32_bf16 v[84:87], v[170:173], v[204:207], v[84:87]
	v_mfma_f32_16x16x32_bf16 v[72:75], v[162:165], v[224:227], v[72:75]
	v_mfma_f32_16x16x32_bf16 v[68:71], v[170:173], v[224:227], v[68:71]
	v_mfma_f32_16x16x32_bf16 v[120:123], v[166:169], v[182:185], v[120:123]
	v_mfma_f32_16x16x32_bf16 v[116:119], v[174:177], v[182:185], v[116:119]
	v_mfma_f32_16x16x32_bf16 v[104:107], v[166:169], v[190:193], v[104:107]
	v_mfma_f32_16x16x32_bf16 v[100:103], v[174:177], v[190:193], v[100:103]
	v_mfma_f32_16x16x32_bf16 v[88:91], v[166:169], v[220:223], v[88:91]
	v_mfma_f32_16x16x32_bf16 v[84:87], v[174:177], v[220:223], v[84:87]
	v_mfma_f32_16x16x32_bf16 v[72:75], v[166:169], v[228:231], v[72:75]
	v_mfma_f32_16x16x32_bf16 v[68:71], v[174:177], v[228:231], v[68:71]
	s_setprio 0
	s_barrier
	s_add_i32 s69, s69, s56
	v_lshl_add_u64 v[194:195], s[44:45], 0, v[2:3]
	s_mov_b32 m0, s69
	ds_read_b128 v[178:181], v149 offset:16384
	ds_read_b128 v[182:185], v149 offset:17408
	ds_read_b128 v[186:189], v149 offset:18432
	ds_read_b128 v[190:193], v149 offset:19456
	ds_read_b128 v[204:207], v149 offset:20480
	ds_read_b128 v[220:223], v149 offset:21504
	ds_read_b128 v[224:227], v149 offset:22528
	ds_read_b128 v[228:231], v149 offset:23552
	global_load_lds_dwordx4 v[194:195], off
	s_add_i32 m0, s69, 0x2000
	s_add_u32 s70, s44, 0x40000
	v_lshl_add_u64 v[196:197], s[44:45], 0, v[136:137]
	s_addc_u32 s71, s45, 0
	s_add_i32 s69, s73, s56
	global_load_lds_dwordx4 v[196:197], off
	v_lshl_add_u64 v[232:233], s[70:71], 0, v[2:3]
	s_mov_b32 m0, s69
	v_lshl_add_u64 v[234:235], s[46:47], 0, v[134:135]
	global_load_lds_dwordx4 v[232:233], off
	v_lshl_add_u64 v[232:233], s[70:71], 0, v[136:137]
	s_add_i32 m0, s69, 0x2000
	s_nop 0
	global_load_lds_dwordx4 v[232:233], off
	v_lshl_add_u64 v[232:233], s[46:47], 0, v[132:133]
	s_mov_b32 m0, s58
	s_nop 0
	global_load_lds_dwordx4 v[232:233], off
	s_mov_b32 m0, s59
	s_nop 0
	global_load_lds_dwordx4 v[234:235], off
	s_waitcnt vmcnt(8)
	s_waitcnt lgkmcnt(0)
	s_barrier
; #define PG8_STAGE(bufoff, gbase, voff) do { _Pragma("unroll") for (int _i = 0; _i < 2; ++_i) \
;         __builtin_amdgcn_global_load_lds((const unsigned*)((const char*)(gbase) + (voff)[_i]), (PG8_LAS unsigned*)(lds + (bufoff) + ldsw + _i * 8192), 16, 0, 0); } while (0)
; #define PG8_LDA(dst, b, h) do { _Pragma("unroll") for (int m = 0; m < 4; ++m) _Pragma("unroll") for (int k = 0; k < 2; ++k) dst[m][k] = *(const PG8_LAS bf16x8*)(lds + PG8_SA(b, h) + aoff + m * 2048 + k * 1024); } while (0)
; #define PG8_LDB(dst, b, h) do { _Pragma("unroll") for (int n = 0; n < 2; ++n) _Pragma("unroll") for (int k = 0; k < 2; ++k) dst[n][k] = *(const PG8_LAS bf16x8*)(lds + PG8_SB(b, h) + boff + n * 2048 + k * 1024); } while (0)
; #define PG8_MMA(ai, bj, At, Bt) do { __builtin_amdgcn_s_setprio(1); _Pragma("unroll") for (int m = 0; m < 4; ++m) _Pragma("unroll") for (int n = 0; n < 2; ++n) _Pragma("unroll") for (int k = 0; k < 2; ++k) \
;         acc[ai][bj][m][n] = __builtin_amdgcn_mfma_f32_16x16x32_bf16(Bt[n][k], At[m][k], acc[ai][bj][m][n], 0, 0, 0); __builtin_amdgcn_s_setprio(0); } while (0)
; #define PG8_WAIT_V(n) asm volatile("s_waitcnt vmcnt(" #n ")" ::: "memory")
; #define PG8_WAIT_L(n) asm volatile("s_waitcnt lgkmcnt(" #n ")" ::: "memory")
; #define PG8_BAR __builtin_amdgcn_s_barrier()
; #define PG8_SCHED __builtin_amdgcn_sched_barrier(0)
; template <class Epi, class Sched, bool ALIGN_EPI = false, bool SP2 = false>
; __device__ __forceinline__ void gemm_phase(PG8_LAS unsigned char* lds, const Gemm g, const Sched& S, const Epi& E) {
;     ...
;             PG8_WAIT_V(8); PG8_WAIT_L(0); PG8_BAR; PG8_MMA(1, 0, At, B0); PG8_MMA(1, 1, At, B1); PG8_BAR; PG8_SCHED;
;             PG8_LDB(B0, 1, 0); PG8_LDB(B1, 1, 1); PG8_SCHED; PG8_LDA(At, 1, 0); PG8_STAGE(PG8_SA(0, 1), a2 + hstep, voffA);
;             PG8_WAIT_V(8); PG8_WAIT_L(0); PG8_BAR; PG8_MMA(0, 0, At, B0); PG8_MMA(0, 1, At, B1); PG8_BAR; PG8_SCHED;
	s_setprio 1
	s_waitcnt lgkmcnt(0)
	v_mfma_f32_16x16x32_bf16 v[64:67], v[142:145], v[178:181], v[64:67]
	v_mfma_f32_16x16x32_bf16 v[60:63], v[154:157], v[178:181], v[60:63]
	v_mfma_f32_16x16x32_bf16 v[48:51], v[142:145], v[186:189], v[48:51]
	v_mfma_f32_16x16x32_bf16 v[44:47], v[154:157], v[186:189], v[44:47]
	v_mfma_f32_16x16x32_bf16 v[32:35], v[142:145], v[204:207], v[32:35]
	v_mfma_f32_16x16x32_bf16 v[28:31], v[154:157], v[204:207], v[28:31]
	v_mfma_f32_16x16x32_bf16 v[16:19], v[142:145], v[224:227], v[16:19]
	v_mfma_f32_16x16x32_bf16 v[12:15], v[154:157], v[224:227], v[12:15]
	v_mfma_f32_16x16x32_bf16 v[64:67], v[150:153], v[182:185], v[64:67]
	v_mfma_f32_16x16x32_bf16 v[60:63], v[158:161], v[182:185], v[60:63]
	v_mfma_f32_16x16x32_bf16 v[48:51], v[150:153], v[190:193], v[48:51]
	v_mfma_f32_16x16x32_bf16 v[44:47], v[158:161], v[190:193], v[44:47]
	v_mfma_f32_16x16x32_bf16 v[32:35], v[150:153], v[220:223], v[32:35]
	v_mfma_f32_16x16x32_bf16 v[28:31], v[158:161], v[220:223], v[28:31]
	v_mfma_f32_16x16x32_bf16 v[16:19], v[150:153], v[228:231], v[16:19]
	v_mfma_f32_16x16x32_bf16 v[12:15], v[158:161], v[228:231], v[12:15]
	s_setprio 0
	s_setprio 1
	v_mfma_f32_16x16x32_bf16 v[56:59], v[162:165], v[178:181], v[56:59]
	v_mfma_f32_16x16x32_bf16 v[52:55], v[170:173], v[178:181], v[52:55]
	v_mfma_f32_16x16x32_bf16 v[40:43], v[162:165], v[186:189], v[40:43]
	v_mfma_f32_16x16x32_bf16 v[36:39], v[170:173], v[186:189], v[36:39]
	v_mfma_f32_16x16x32_bf16 v[24:27], v[162:165], v[204:207], v[24:27]
	v_mfma_f32_16x16x32_bf16 v[20:23], v[170:173], v[204:207], v[20:23]
	v_mfma_f32_16x16x32_bf16 v[8:11], v[162:165], v[224:227], v[8:11]
	v_mfma_f32_16x16x32_bf16 v[4:7], v[170:173], v[224:227], v[4:7]
	v_mfma_f32_16x16x32_bf16 v[56:59], v[166:169], v[182:185], v[56:59]
	v_mfma_f32_16x16x32_bf16 v[52:55], v[174:177], v[182:185], v[52:55]
	v_mfma_f32_16x16x32_bf16 v[40:43], v[166:169], v[190:193], v[40:43]
	v_mfma_f32_16x16x32_bf16 v[36:39], v[174:177], v[190:193], v[36:39]
	v_mfma_f32_16x16x32_bf16 v[24:27], v[166:169], v[220:223], v[24:27]
	v_mfma_f32_16x16x32_bf16 v[20:23], v[174:177], v[220:223], v[20:23]
	v_mfma_f32_16x16x32_bf16 v[8:11], v[166:169], v[228:231], v[8:11]
	v_mfma_f32_16x16x32_bf16 v[4:7], v[174:177], v[228:231], v[4:7]
	s_setprio 0
	s_barrier
	s_add_i32 s69, 0, 0x18000
	s_add_i32 s70, 0, 0x1c000
	v_add_u32_e32 v158, s69, v147
	v_add_u32_e32 v174, s70, v147
	ds_read_b128 v[142:145], v158
	ds_read_b128 v[150:153], v158 offset:1024
	ds_read_b128 v[154:157], v158 offset:2048
	ds_read_b128 v[158:161], v158 offset:3072
	ds_read_b128 v[162:165], v174
	ds_read_b128 v[166:169], v174 offset:1024
	ds_read_b128 v[170:173], v174 offset:2048
	ds_read_b128 v[174:177], v174 offset:3072
	s_add_u32 s46, s46, 0x40000
	s_addc_u32 s47, s47, 0
	s_mov_b32 m0, s60
	v_lshl_add_u64 v[236:237], s[46:47], 0, v[132:133]
	ds_read_b128 v[178:181], v149 offset:32768
	ds_read_b128 v[182:185], v149 offset:33792
	ds_read_b128 v[186:189], v149 offset:34816
	ds_read_b128 v[190:193], v149 offset:35840
	ds_read_b128 v[204:207], v149 offset:36864
	ds_read_b128 v[220:223], v149 offset:37888
	ds_read_b128 v[224:227], v149 offset:38912
	ds_read_b128 v[228:231], v149 offset:39936
	global_load_lds_dwordx4 v[236:237], off
	v_lshl_add_u64 v[236:237], s[46:47], 0, v[134:135]
	s_mov_b32 m0, s61
	s_nop 0
	global_load_lds_dwordx4 v[236:237], off
	s_waitcnt vmcnt(8)
	s_waitcnt lgkmcnt(0)
	s_barrier
	s_setprio 1
	s_waitcnt lgkmcnt(0)
	v_mfma_f32_16x16x32_bf16 v[128:131], v[142:145], v[178:181], v[128:131]
	v_mfma_f32_16x16x32_bf16 v[124:127], v[154:157], v[178:181], v[124:127]
	v_mfma_f32_16x16x32_bf16 v[112:115], v[142:145], v[186:189], v[112:115]
	v_mfma_f32_16x16x32_bf16 v[108:111], v[154:157], v[186:189], v[108:111]
	v_mfma_f32_16x16x32_bf16 v[96:99], v[142:145], v[204:207], v[96:99]
	v_mfma_f32_16x16x32_bf16 v[92:95], v[154:157], v[204:207], v[92:95]
	v_mfma_f32_16x16x32_bf16 v[80:83], v[142:145], v[224:227], v[80:83]
	v_mfma_f32_16x16x32_bf16 v[76:79], v[154:157], v[224:227], v[76:79]
	v_mfma_f32_16x16x32_bf16 v[128:131], v[150:153], v[182:185], v[128:131]
	v_mfma_f32_16x16x32_bf16 v[124:127], v[158:161], v[182:185], v[124:127]
	v_mfma_f32_16x16x32_bf16 v[112:115], v[150:153], v[190:193], v[112:115]
	v_mfma_f32_16x16x32_bf16 v[108:111], v[158:161], v[190:193], v[108:111]
	v_mfma_f32_16x16x32_bf16 v[96:99], v[150:153], v[220:223], v[96:99]
	v_mfma_f32_16x16x32_bf16 v[92:95], v[158:161], v[220:223], v[92:95]
	v_mfma_f32_16x16x32_bf16 v[80:83], v[150:153], v[228:231], v[80:83]
	v_mfma_f32_16x16x32_bf16 v[76:79], v[158:161], v[228:231], v[76:79]
	s_setprio 0
	s_setprio 1
	v_mfma_f32_16x16x32_bf16 v[120:123], v[162:165], v[178:181], v[120:123]
	v_mfma_f32_16x16x32_bf16 v[116:119], v[170:173], v[178:181], v[116:119]
	v_mfma_f32_16x16x32_bf16 v[104:107], v[162:165], v[186:189], v[104:107]
	v_mfma_f32_16x16x32_bf16 v[100:103], v[170:173], v[186:189], v[100:103]
	v_mfma_f32_16x16x32_bf16 v[88:91], v[162:165], v[204:207], v[88:91]
	v_mfma_f32_16x16x32_bf16 v[84:87], v[170:173], v[204:207], v[84:87]
	v_mfma_f32_16x16x32_bf16 v[72:75], v[162:165], v[224:227], v[72:75]
	v_mfma_f32_16x16x32_bf16 v[68:71], v[170:173], v[224:227], v[68:71]
	v_mfma_f32_16x16x32_bf16 v[120:123], v[166:169], v[182:185], v[120:123]
	v_mfma_f32_16x16x32_bf16 v[116:119], v[174:177], v[182:185], v[116:119]
	v_mfma_f32_16x16x32_bf16 v[104:107], v[166:169], v[190:193], v[104:107]
	v_mfma_f32_16x16x32_bf16 v[100:103], v[174:177], v[190:193], v[100:103]
	v_mfma_f32_16x16x32_bf16 v[88:91], v[166:169], v[220:223], v[88:91]
	v_mfma_f32_16x16x32_bf16 v[84:87], v[174:177], v[220:223], v[84:87]
	v_mfma_f32_16x16x32_bf16 v[72:75], v[166:169], v[228:231], v[72:75]
	v_mfma_f32_16x16x32_bf16 v[68:71], v[174:177], v[228:231], v[68:71]
	s_setprio 0
	s_barrier
; #define PG8_STAGE(bufoff, gbase, voff) do { _Pragma("unroll") for (int _i = 0; _i < 2; ++_i) \
;         __builtin_amdgcn_global_load_lds((const unsigned*)((const char*)(gbase) + (voff)[_i]), (PG8_LAS unsigned*)(lds + (bufoff) + ldsw + _i * 8192), 16, 0, 0); } while (0)
; #define PG8_LDA(dst, b, h) do { _Pragma("unroll") for (int m = 0; m < 4; ++m) _Pragma("unroll") for (int k = 0; k < 2; ++k) dst[m][k] = *(const PG8_LAS bf16x8*)(lds + PG8_SA(b, h) + aoff + m * 2048 + k * 1024); } while (0)
; #define PG8_MMA(ai, bj, At, Bt) do { __builtin_amdgcn_s_setprio(1); _Pragma("unroll") for (int m = 0; m < 4; ++m) _Pragma("unroll") for (int n = 0; n < 2; ++n) _Pragma("unroll") for (int k = 0; k < 2; ++k) \
;         acc[ai][bj][m][n] = __builtin_amdgcn_mfma_f32_16x16x32_bf16(Bt[n][k], At[m][k], acc[ai][bj][m][n], 0, 0, 0); __builtin_amdgcn_s_setprio(0); } while (0)
; #define PG8_WAIT_V(n) asm volatile("s_waitcnt vmcnt(" #n ")" ::: "memory")
; #define PG8_WAIT_L(n) asm volatile("s_waitcnt lgkmcnt(" #n ")" ::: "memory")
; #define PG8_BAR __builtin_amdgcn_s_barrier()
; #define PG8_SCHED __builtin_amdgcn_sched_barrier(0)
; template <class Epi, class Sched, bool ALIGN_EPI = false, bool SP2 = false>
; __device__ __forceinline__ void gemm_phase(PG8_LAS unsigned char* lds, const Gemm g, const Sched& S, const Epi& E) {
;     ...
;         for (int t = 0; t < nt; t += 2) {
;             const bool last = (t == nt - 2);
;     ...
;             PG8_LDA(At, 1, 1); PG8_STAGE(PG8_SB(1, 0), b3, voffB); PG8_STAGE(PG8_SB(1, 1), b3 + hstep, voffB); PG8_STAGE(PG8_SA(1, 0), a3, voffA);
;             PG8_WAIT_V(8); PG8_WAIT_L(0); PG8_BAR; PG8_MMA(1, 0, At, B0); PG8_MMA(1, 1, At, B1); PG8_BAR; PG8_SCHED;
	s_add_i32 s46, s69, s56
	v_lshl_add_u64 v[194:195], v[194:195], 0, s[92:93]
	s_mov_b32 m0, s46
	ds_read_b128 v[178:181], v149 offset:49152
	ds_read_b128 v[182:185], v149 offset:50176
	ds_read_b128 v[186:189], v149 offset:51200
	ds_read_b128 v[190:193], v149 offset:52224
	ds_read_b128 v[204:207], v149 offset:53248
	ds_read_b128 v[220:223], v149 offset:54272
	ds_read_b128 v[224:227], v149 offset:55296
	ds_read_b128 v[228:231], v149 offset:56320
	global_load_lds_dwordx4 v[194:195], off
	s_add_i32 m0, s46, 0x2000
	s_add_u32 s44, s44, 0x40080
	v_lshl_add_u64 v[194:195], v[196:197], 0, s[92:93]
	s_addc_u32 s45, s45, 0
	s_add_i32 s46, s70, s56
	global_load_lds_dwordx4 v[194:195], off
	v_lshl_add_u64 v[194:195], s[44:45], 0, v[2:3]
	s_mov_b32 m0, s46
	s_nop 0
	global_load_lds_dwordx4 v[194:195], off
	v_lshl_add_u64 v[194:195], s[44:45], 0, v[136:137]
	s_add_i32 m0, s46, 0x2000
	s_nop 0
	global_load_lds_dwordx4 v[194:195], off
	v_lshl_add_u64 v[194:195], v[232:233], 0, s[92:93]
	s_mov_b32 m0, s62
	s_nop 0
	global_load_lds_dwordx4 v[194:195], off
	v_lshl_add_u64 v[194:195], v[234:235], 0, s[92:93]
	s_mov_b32 m0, s63
	s_nop 0
	global_load_lds_dwordx4 v[194:195], off
	s_waitcnt vmcnt(8)
	s_waitcnt lgkmcnt(0)
	s_barrier
	s_setprio 1
	s_waitcnt lgkmcnt(0)
	v_mfma_f32_16x16x32_bf16 v[64:67], v[142:145], v[178:181], v[64:67]
	v_mfma_f32_16x16x32_bf16 v[60:63], v[154:157], v[178:181], v[60:63]
	v_mfma_f32_16x16x32_bf16 v[48:51], v[142:145], v[186:189], v[48:51]
	v_mfma_f32_16x16x32_bf16 v[44:47], v[154:157], v[186:189], v[44:47]
	v_mfma_f32_16x16x32_bf16 v[32:35], v[142:145], v[204:207], v[32:35]
	v_mfma_f32_16x16x32_bf16 v[28:31], v[154:157], v[204:207], v[28:31]
	v_mfma_f32_16x16x32_bf16 v[16:19], v[142:145], v[224:227], v[16:19]
	v_mfma_f32_16x16x32_bf16 v[12:15], v[154:157], v[224:227], v[12:15]
	v_mfma_f32_16x16x32_bf16 v[64:67], v[150:153], v[182:185], v[64:67]
	v_mfma_f32_16x16x32_bf16 v[60:63], v[158:161], v[182:185], v[60:63]
	v_mfma_f32_16x16x32_bf16 v[48:51], v[150:153], v[190:193], v[48:51]
	v_mfma_f32_16x16x32_bf16 v[44:47], v[158:161], v[190:193], v[44:47]
	v_mfma_f32_16x16x32_bf16 v[32:35], v[150:153], v[220:223], v[32:35]
	v_mfma_f32_16x16x32_bf16 v[28:31], v[158:161], v[220:223], v[28:31]
	v_mfma_f32_16x16x32_bf16 v[16:19], v[150:153], v[228:231], v[16:19]
	v_mfma_f32_16x16x32_bf16 v[12:15], v[158:161], v[228:231], v[12:15]
	s_setprio 0
	s_setprio 1
	v_mfma_f32_16x16x32_bf16 v[56:59], v[162:165], v[178:181], v[56:59]
	v_mfma_f32_16x16x32_bf16 v[52:55], v[170:173], v[178:181], v[52:55]
	v_mfma_f32_16x16x32_bf16 v[40:43], v[162:165], v[186:189], v[40:43]
	v_mfma_f32_16x16x32_bf16 v[36:39], v[170:173], v[186:189], v[36:39]
	v_mfma_f32_16x16x32_bf16 v[24:27], v[162:165], v[204:207], v[24:27]
	v_mfma_f32_16x16x32_bf16 v[20:23], v[170:173], v[204:207], v[20:23]
	v_mfma_f32_16x16x32_bf16 v[8:11], v[162:165], v[224:227], v[8:11]
	v_mfma_f32_16x16x32_bf16 v[4:7], v[170:173], v[224:227], v[4:7]
	v_mfma_f32_16x16x32_bf16 v[56:59], v[166:169], v[182:185], v[56:59]
	v_mfma_f32_16x16x32_bf16 v[52:55], v[174:177], v[182:185], v[52:55]
	v_mfma_f32_16x16x32_bf16 v[40:43], v[166:169], v[190:193], v[40:43]
	v_mfma_f32_16x16x32_bf16 v[36:39], v[174:177], v[190:193], v[36:39]
	v_mfma_f32_16x16x32_bf16 v[24:27], v[166:169], v[220:223], v[24:27]
	v_mfma_f32_16x16x32_bf16 v[20:23], v[174:177], v[220:223], v[20:23]
	v_mfma_f32_16x16x32_bf16 v[8:11], v[166:169], v[228:231], v[8:11]
	v_mfma_f32_16x16x32_bf16 v[4:7], v[174:177], v[228:231], v[4:7]
	s_setprio 0
	s_barrier
	s_add_i32 s68, s68, 2
	s_add_u32 s42, s42, 0x100
	s_addc_u32 s43, s43, 0
	s_add_u32 s66, s66, 0x100
	s_addc_u32 s67, s67, 0
	s_cmp_gt_u32 s68, 13
	s_cbranch_scc0 .LBB0_685
	s_and_b64 vcc, exec, s[28:29]
	s_cbranch_vccz .LBB0_688
	s_barrier
